# select radix passes: per-key exec-mask toggling replaced by a v_cndmask to a per-lane trash word (no SALU, no exec writes in the histogram loop)
# baseline (speedup 1.0000x reference)
; #define LAS __attribute__((address_space(3)))
; DI void select_unit(unsigned char* ws, LAS unsigned char* lds, int b, int blk, const float* scratch, int wave) {
;     ...
;         unsigned prefix = 0u, pmask = 0u; int kk = TOPK; bool simple = false;
;         for (int pass = 0; pass < 4; ++pass) {
;             const int shift = 24 - 8 * pass;
; #pragma unroll
;             for (int z = 0; z < 8; ++z) *(LAS v4u*)(hist + 4 * (lane + 64 * z)) = (v4u){0u, 0u, 0u, 0u};
;             LAS unsigned* hc = hist + 256 * (lane & 7);
.LBB0_653:
	v_lshlrev_b32_e32 v1, 10, v0
	v_lshlrev_b32_e32 v19, 4, v0
	v_and_b32_e32 v1, 0x1c00, v1
	v_readlane_b32 s0, v254, 33
	v_cmp_gt_i32_e64 s[66:67], 63, v0
	v_cmp_gt_i32_e64 s[68:69], 62, v0
	v_add_u32_e32 v21, s0, v1
	v_cmp_gt_i32_e64 s[70:71], 60, v0
	v_cmp_gt_i32_e64 s[72:73], 56, v0
	v_cmp_gt_i32_e64 s[74:75], 48, v0
	v_cmp_gt_i32_e64 s[76:77], 32, v0
	v_mov_b32_e32 v46, 0x100
	v_mov_b32_e32 v1, 0
	s_mov_b32 s54, 24
	s_mov_b64 s[46:47], 0
	s_mov_b32 s55, 0
	v_add_u32_e32 v22, s0, v19
	s_lshr_b32 s0, s0, 5
	s_add_i32 s0, s0, 0x10000
	v_lshl_add_u32 v248, v0, 2, s0
	s_branch .LBB0_657

; #define LAS __attribute__((address_space(3)))
; DI void select_unit(unsigned char* ws, LAS unsigned char* lds, int b, int blk, const float* scratch, int wave) {
;     ...
;             for (int z = 0; z < 8; ++z) *(LAS v4u*)(hist + 4 * (lane + 64 * z)) = (v4u){0u, 0u, 0u, 0u};
;             LAS unsigned* hc = hist + 256 * (lane & 7);
; #pragma unroll
;             for (int j = 0; j < 32; ++j) if (64 * j < n4) {
; #pragma unroll
;                 for (int c = 0; c < 4; ++c) { const unsigned u = key[j][c]; if ((u & pmask) == prefix) __hip_atomic_fetch_add(hc + ((u >> shift) & 255u), 1u, __ATOMIC_RELAXED, __HIP_MEMORY_SCOPE_WORKGROUP); } }
.LBB0_657:
	v_and_b32_e32 v19, s55, v133
	v_cmp_eq_u32_e32 vcc, v19, v1
	ds_write_b128 v22, v[178:181] offset:34816
	ds_write_b128 v22, v[178:181] offset:35840
	ds_write_b128 v22, v[178:181] offset:36864
	ds_write_b128 v22, v[178:181] offset:37888
	ds_write_b128 v22, v[178:181] offset:38912
	ds_write_b128 v22, v[178:181] offset:39936
	ds_write_b128 v22, v[178:181] offset:40960
	ds_write_b128 v22, v[178:181] offset:41984
	v_bfe_u32 v19, v133, s54, 8
	v_lshl_add_u32 v19, v19, 2, v21
	v_cndmask_b32_e32 v19, v248, v19, vcc
	ds_add_u32 v19, v172 offset:34816
	v_and_b32_e32 v19, s55, v134
	v_cmp_eq_u32_e32 vcc, v19, v1
	v_bfe_u32 v19, v134, s54, 8
	v_lshl_add_u32 v19, v19, 2, v21
	v_cndmask_b32_e32 v19, v248, v19, vcc
	ds_add_u32 v19, v172 offset:34816
	v_and_b32_e32 v19, s55, v135
	v_cmp_eq_u32_e32 vcc, v19, v1
	v_bfe_u32 v19, v135, s54, 8
	v_lshl_add_u32 v19, v19, 2, v21
	v_cndmask_b32_e32 v19, v248, v19, vcc
	ds_add_u32 v19, v172 offset:34816
	v_and_b32_e32 v19, s55, v136
	v_cmp_eq_u32_e32 vcc, v19, v1
	v_bfe_u32 v19, v136, s54, 8
	v_lshl_add_u32 v19, v19, 2, v21
	v_cndmask_b32_e32 v19, v248, v19, vcc
	ds_add_u32 v19, v172 offset:34816
	v_and_b32_e32 v19, s55, v127
	v_cmp_eq_u32_e32 vcc, v19, v1
	v_bfe_u32 v19, v127, s54, 8
	v_lshl_add_u32 v19, v19, 2, v21
	v_cndmask_b32_e32 v19, v248, v19, vcc
	ds_add_u32 v19, v172 offset:34816
	v_and_b32_e32 v19, s55, v130
	v_cmp_eq_u32_e32 vcc, v19, v1
	v_bfe_u32 v19, v130, s54, 8
	v_lshl_add_u32 v19, v19, 2, v21
	v_cndmask_b32_e32 v19, v248, v19, vcc
	ds_add_u32 v19, v172 offset:34816
	v_and_b32_e32 v19, s55, v129
	v_cmp_eq_u32_e32 vcc, v19, v1
	v_bfe_u32 v19, v129, s54, 8
	v_lshl_add_u32 v19, v19, 2, v21
	v_cndmask_b32_e32 v19, v248, v19, vcc
	ds_add_u32 v19, v172 offset:34816
	v_and_b32_e32 v19, s55, v128
	v_cmp_eq_u32_e32 vcc, v19, v1
	v_bfe_u32 v19, v128, s54, 8
	v_lshl_add_u32 v19, v19, 2, v21
	v_cndmask_b32_e32 v19, v248, v19, vcc
	ds_add_u32 v19, v172 offset:34816
	v_cndmask_b32_e64 v19, 0, 1, s[2:3]
	v_cmp_ne_u32_e64 s[64:65], 1, v19
	s_andn2_b64 vcc, exec, s[2:3]
	s_cbranch_vccnz .LBB0_693
	v_and_b32_e32 v19, s55, v126
	v_cmp_eq_u32_e32 vcc, v19, v1
	v_bfe_u32 v19, v126, s54, 8
	v_lshl_add_u32 v19, v19, 2, v21
	v_cndmask_b32_e32 v19, v248, v19, vcc
	ds_add_u32 v19, v172 offset:34816
	v_and_b32_e32 v19, s55, v125
	v_cmp_eq_u32_e32 vcc, v19, v1
	v_bfe_u32 v19, v125, s54, 8
	v_lshl_add_u32 v19, v19, 2, v21
	v_cndmask_b32_e32 v19, v248, v19, vcc
	ds_add_u32 v19, v172 offset:34816
	v_and_b32_e32 v19, s55, v124
	v_cmp_eq_u32_e32 vcc, v19, v1
	v_bfe_u32 v19, v124, s54, 8
	v_lshl_add_u32 v19, v19, 2, v21
	v_cndmask_b32_e32 v19, v248, v19, vcc
	ds_add_u32 v19, v172 offset:34816
	v_and_b32_e32 v19, s55, v123
	v_cmp_eq_u32_e32 vcc, v19, v1
	v_bfe_u32 v19, v123, s54, 8
	v_lshl_add_u32 v19, v19, 2, v21
	v_cndmask_b32_e32 v19, v248, v19, vcc
	ds_add_u32 v19, v172 offset:34816
	v_cndmask_b32_e64 v19, 0, 1, s[84:85]
	v_cmp_ne_u32_e64 s[62:63], 1, v19
	s_andn2_b64 vcc, exec, s[84:85]
	s_cbranch_vccz .LBB0_694

; DI void select_unit(unsigned char* ws, LAS unsigned char* lds, int b, int blk, const float* scratch, int wave) {
;     ...
;             for (int j = 0; j < 32; ++j) if (64 * j < n4) {
; #pragma unroll
;                 for (int c = 0; c < 4; ++c) { const unsigned u = key[j][c]; if ((u & pmask) == prefix) __hip_atomic_fetch_add(hc + ((u >> shift) & 255u), 1u, __ATOMIC_RELAXED, __HIP_MEMORY_SCOPE_WORKGROUP); } }
.LBB0_684:
	v_and_b32_e32 v19, s55, v118
	v_cmp_eq_u32_e32 vcc, v19, v1
	v_bfe_u32 v19, v118, s54, 8
	v_lshl_add_u32 v19, v19, 2, v21
	v_cndmask_b32_e32 v19, v248, v19, vcc
	ds_add_u32 v19, v172 offset:34816
	v_and_b32_e32 v19, s55, v117
	v_cmp_eq_u32_e32 vcc, v19, v1
	v_bfe_u32 v19, v117, s54, 8
	v_lshl_add_u32 v19, v19, 2, v21
	v_cndmask_b32_e32 v19, v248, v19, vcc
	ds_add_u32 v19, v172 offset:34816
	v_and_b32_e32 v19, s55, v116
	v_cmp_eq_u32_e32 vcc, v19, v1
	v_bfe_u32 v19, v116, s54, 8
	v_lshl_add_u32 v19, v19, 2, v21
	v_cndmask_b32_e32 v19, v248, v19, vcc
	ds_add_u32 v19, v172 offset:34816
	v_and_b32_e32 v19, s55, v115
	v_cmp_eq_u32_e32 vcc, v19, v1
	v_bfe_u32 v19, v115, s54, 8
	v_lshl_add_u32 v19, v19, 2, v21
	v_cndmask_b32_e32 v19, v248, v19, vcc
	ds_add_u32 v19, v172 offset:34816
	v_cndmask_b32_e64 v19, 0, 1, s[86:87]
	v_cmp_ne_u32_e64 s[58:59], 1, v19
	s_andn2_b64 vcc, exec, s[86:87]
	s_cbranch_vccnz .LBB0_713
	s_branch .LBB0_704

; DI void select_unit(unsigned char* ws, LAS unsigned char* lds, int b, int blk, const float* scratch, int wave) {
;     ...
;             for (int j = 0; j < 32; ++j) if (64 * j < n4) {
; #pragma unroll
;                 for (int c = 0; c < 4; ++c) { const unsigned u = key[j][c]; if ((u & pmask) == prefix) __hip_atomic_fetch_add(hc + ((u >> shift) & 255u), 1u, __ATOMIC_RELAXED, __HIP_MEMORY_SCOPE_WORKGROUP); } }
.LBB0_694:
	v_and_b32_e32 v19, s55, v119
	v_cmp_eq_u32_e32 vcc, v19, v1
	v_bfe_u32 v19, v119, s54, 8
	v_lshl_add_u32 v19, v19, 2, v21
	v_cndmask_b32_e32 v19, v248, v19, vcc
	ds_add_u32 v19, v172 offset:34816
	v_and_b32_e32 v19, s55, v122
	v_cmp_eq_u32_e32 vcc, v19, v1
	v_bfe_u32 v19, v122, s54, 8
	v_lshl_add_u32 v19, v19, 2, v21
	v_cndmask_b32_e32 v19, v248, v19, vcc
	ds_add_u32 v19, v172 offset:34816
	v_and_b32_e32 v19, s55, v121
	v_cmp_eq_u32_e32 vcc, v19, v1
	v_bfe_u32 v19, v121, s54, 8
	v_lshl_add_u32 v19, v19, 2, v21
	v_cndmask_b32_e32 v19, v248, v19, vcc
	ds_add_u32 v19, v172 offset:34816
	v_and_b32_e32 v19, s55, v120
	v_cmp_eq_u32_e32 vcc, v19, v1
	v_bfe_u32 v19, v120, s54, 8
	v_lshl_add_u32 v19, v19, 2, v21
	v_cndmask_b32_e32 v19, v248, v19, vcc
	ds_add_u32 v19, v172 offset:34816
	v_cndmask_b32_e64 v19, 0, 1, s[88:89]
	v_cmp_ne_u32_e64 s[60:61], 1, v19
	s_andn2_b64 vcc, exec, s[88:89]
	s_cbranch_vccz .LBB0_684

; DI void select_unit(unsigned char* ws, LAS unsigned char* lds, int b, int blk, const float* scratch, int wave) {
;     ...
;             for (int j = 0; j < 32; ++j) if (64 * j < n4) {
; #pragma unroll
;                 for (int c = 0; c < 4; ++c) { const unsigned u = key[j][c]; if ((u & pmask) == prefix) __hip_atomic_fetch_add(hc + ((u >> shift) & 255u), 1u, __ATOMIC_RELAXED, __HIP_MEMORY_SCOPE_WORKGROUP); } }
.LBB0_704:
	v_and_b32_e32 v19, s55, v111
	v_cmp_eq_u32_e32 vcc, v19, v1
	v_bfe_u32 v19, v111, s54, 8
	v_lshl_add_u32 v19, v19, 2, v21
	v_cndmask_b32_e32 v19, v248, v19, vcc
	ds_add_u32 v19, v172 offset:34816
	v_and_b32_e32 v19, s55, v114
	v_cmp_eq_u32_e32 vcc, v19, v1
	v_bfe_u32 v19, v114, s54, 8
	v_lshl_add_u32 v19, v19, 2, v21
	v_cndmask_b32_e32 v19, v248, v19, vcc
	ds_add_u32 v19, v172 offset:34816
	v_and_b32_e32 v19, s55, v113
	v_cmp_eq_u32_e32 vcc, v19, v1
	v_bfe_u32 v19, v113, s54, 8
	v_lshl_add_u32 v19, v19, 2, v21
	v_cndmask_b32_e32 v19, v248, v19, vcc
	ds_add_u32 v19, v172 offset:34816
	v_and_b32_e32 v19, s55, v112
	v_cmp_eq_u32_e32 vcc, v19, v1
	v_bfe_u32 v19, v112, s54, 8
	v_lshl_add_u32 v19, v19, 2, v21
	v_cndmask_b32_e32 v19, v248, v19, vcc
	ds_add_u32 v19, v172 offset:34816
.LBB0_713:
	v_cndmask_b32_e64 v19, 0, 1, s[92:93]
	v_cmp_ne_u32_e64 s[0:1], 1, v19
	s_andn2_b64 vcc, exec, s[92:93]
	s_nop 0
	v_writelane_b32 v254, s0, 63
	s_nop 1
	v_writelane_b32 v253, s1, 0
	s_cbranch_vccnz .LBB0_723
	v_and_b32_e32 v19, s55, v110
	v_cmp_eq_u32_e32 vcc, v19, v1
	v_bfe_u32 v19, v110, s54, 8
	v_lshl_add_u32 v19, v19, 2, v21
	v_cndmask_b32_e32 v19, v248, v19, vcc
	ds_add_u32 v19, v172 offset:34816
	v_and_b32_e32 v19, s55, v109
	v_cmp_eq_u32_e32 vcc, v19, v1
	v_bfe_u32 v19, v109, s54, 8
	v_lshl_add_u32 v19, v19, 2, v21
	v_cndmask_b32_e32 v19, v248, v19, vcc
	ds_add_u32 v19, v172 offset:34816
	v_and_b32_e32 v19, s55, v108
	v_cmp_eq_u32_e32 vcc, v19, v1
	v_bfe_u32 v19, v108, s54, 8
	v_lshl_add_u32 v19, v19, 2, v21
	v_cndmask_b32_e32 v19, v248, v19, vcc
	ds_add_u32 v19, v172 offset:34816
	v_and_b32_e32 v19, s55, v107
	v_cmp_eq_u32_e32 vcc, v19, v1
	v_bfe_u32 v19, v107, s54, 8
	v_lshl_add_u32 v19, v19, 2, v21
	v_cndmask_b32_e32 v19, v248, v19, vcc
	ds_add_u32 v19, v172 offset:34816
.LBB0_723:
	v_cndmask_b32_e64 v19, 0, 1, s[78:79]
	v_cmp_ne_u32_e64 s[0:1], 1, v19
	s_andn2_b64 vcc, exec, s[78:79]
	s_nop 0
	v_writelane_b32 v253, s0, 1
	s_nop 1
	v_writelane_b32 v253, s1, 2
	s_cbranch_vccnz .LBB0_733
	v_and_b32_e32 v19, s55, v103
	v_cmp_eq_u32_e32 vcc, v19, v1
	v_bfe_u32 v19, v103, s54, 8
	v_lshl_add_u32 v19, v19, 2, v21
	v_cndmask_b32_e32 v19, v248, v19, vcc
	ds_add_u32 v19, v172 offset:34816
	v_and_b32_e32 v19, s55, v106
	v_cmp_eq_u32_e32 vcc, v19, v1
	v_bfe_u32 v19, v106, s54, 8
	v_lshl_add_u32 v19, v19, 2, v21
	v_cndmask_b32_e32 v19, v248, v19, vcc
	ds_add_u32 v19, v172 offset:34816
	v_and_b32_e32 v19, s55, v105
	v_cmp_eq_u32_e32 vcc, v19, v1
	v_bfe_u32 v19, v105, s54, 8
	v_lshl_add_u32 v19, v19, 2, v21
	v_cndmask_b32_e32 v19, v248, v19, vcc
	ds_add_u32 v19, v172 offset:34816
	v_and_b32_e32 v19, s55, v104
	v_cmp_eq_u32_e32 vcc, v19, v1
	v_bfe_u32 v19, v104, s54, 8
	v_lshl_add_u32 v19, v19, 2, v21
	v_cndmask_b32_e32 v19, v248, v19, vcc
	ds_add_u32 v19, v172 offset:34816
.LBB0_733:
	v_cndmask_b32_e64 v19, 0, 1, s[94:95]
	v_cmp_ne_u32_e64 s[52:53], 1, v19
	s_andn2_b64 vcc, exec, s[94:95]
	s_cbranch_vccnz .LBB0_743
	v_and_b32_e32 v19, s55, v102
	v_cmp_eq_u32_e32 vcc, v19, v1
	v_bfe_u32 v19, v102, s54, 8
	v_lshl_add_u32 v19, v19, 2, v21
	v_cndmask_b32_e32 v19, v248, v19, vcc
	ds_add_u32 v19, v172 offset:34816
	v_and_b32_e32 v19, s55, v101
	v_cmp_eq_u32_e32 vcc, v19, v1
	v_bfe_u32 v19, v101, s54, 8
	v_lshl_add_u32 v19, v19, 2, v21
	v_cndmask_b32_e32 v19, v248, v19, vcc
	ds_add_u32 v19, v172 offset:34816
	v_and_b32_e32 v19, s55, v100
	v_cmp_eq_u32_e32 vcc, v19, v1
	v_bfe_u32 v19, v100, s54, 8
	v_lshl_add_u32 v19, v19, 2, v21
	v_cndmask_b32_e32 v19, v248, v19, vcc
	ds_add_u32 v19, v172 offset:34816
	v_and_b32_e32 v19, s55, v99
	v_cmp_eq_u32_e32 vcc, v19, v1
	v_bfe_u32 v19, v99, s54, 8
	v_lshl_add_u32 v19, v19, 2, v21
	v_cndmask_b32_e32 v19, v248, v19, vcc
	ds_add_u32 v19, v172 offset:34816
.LBB0_743:
	v_cndmask_b32_e64 v19, 0, 1, s[96:97]
	v_cmp_ne_u32_e64 s[0:1], 1, v19
	s_andn2_b64 vcc, exec, s[96:97]
	s_nop 0
	v_writelane_b32 v253, s0, 3
	s_nop 1
	v_writelane_b32 v253, s1, 4
	s_cbranch_vccnz .LBB0_753
	v_and_b32_e32 v19, s55, v95
	v_cmp_eq_u32_e32 vcc, v19, v1
	v_bfe_u32 v19, v95, s54, 8
	v_lshl_add_u32 v19, v19, 2, v21
	v_cndmask_b32_e32 v19, v248, v19, vcc
	ds_add_u32 v19, v172 offset:34816
	v_and_b32_e32 v19, s55, v98
	v_cmp_eq_u32_e32 vcc, v19, v1
	v_bfe_u32 v19, v98, s54, 8
	v_lshl_add_u32 v19, v19, 2, v21
	v_cndmask_b32_e32 v19, v248, v19, vcc
	ds_add_u32 v19, v172 offset:34816
	v_and_b32_e32 v19, s55, v97
	v_cmp_eq_u32_e32 vcc, v19, v1
	v_bfe_u32 v19, v97, s54, 8
	v_lshl_add_u32 v19, v19, 2, v21
	v_cndmask_b32_e32 v19, v248, v19, vcc
	ds_add_u32 v19, v172 offset:34816
	v_and_b32_e32 v19, s55, v96
	v_cmp_eq_u32_e32 vcc, v19, v1
	v_bfe_u32 v19, v96, s54, 8
	v_lshl_add_u32 v19, v19, 2, v21
	v_cndmask_b32_e32 v19, v248, v19, vcc
	ds_add_u32 v19, v172 offset:34816
.LBB0_753:
	v_cndmask_b32_e64 v19, 0, 1, s[80:81]
	v_cmp_ne_u32_e64 s[0:1], 1, v19
	s_andn2_b64 vcc, exec, s[80:81]
	s_nop 0
	v_writelane_b32 v253, s0, 5
	s_nop 1
	v_writelane_b32 v253, s1, 6
	s_cbranch_vccnz .LBB0_763
	v_and_b32_e32 v19, s55, v94
	v_cmp_eq_u32_e32 vcc, v19, v1
	v_bfe_u32 v19, v94, s54, 8
	v_lshl_add_u32 v19, v19, 2, v21
	v_cndmask_b32_e32 v19, v248, v19, vcc
	ds_add_u32 v19, v172 offset:34816
	v_and_b32_e32 v19, s55, v93
	v_cmp_eq_u32_e32 vcc, v19, v1
	v_bfe_u32 v19, v93, s54, 8
	v_lshl_add_u32 v19, v19, 2, v21
	v_cndmask_b32_e32 v19, v248, v19, vcc
	ds_add_u32 v19, v172 offset:34816
	v_and_b32_e32 v19, s55, v92
	v_cmp_eq_u32_e32 vcc, v19, v1
	v_bfe_u32 v19, v92, s54, 8
	v_lshl_add_u32 v19, v19, 2, v21
	v_cndmask_b32_e32 v19, v248, v19, vcc
	ds_add_u32 v19, v172 offset:34816
	v_and_b32_e32 v19, s55, v91
	v_cmp_eq_u32_e32 vcc, v19, v1
	v_bfe_u32 v19, v91, s54, 8
	v_lshl_add_u32 v19, v19, 2, v21
	v_cndmask_b32_e32 v19, v248, v19, vcc
	ds_add_u32 v19, v172 offset:34816
; DI void select_unit(unsigned char* ws, LAS unsigned char* lds, int b, int blk, const float* scratch, int wave) {
;     ...
;             for (int j = 0; j < 32; ++j) if (64 * j < n4) {
; #pragma unroll
;                 for (int c = 0; c < 4; ++c) { const unsigned u = key[j][c]; if ((u & pmask) == prefix) __hip_atomic_fetch_add(hc + ((u >> shift) & 255u), 1u, __ATOMIC_RELAXED, __HIP_MEMORY_SCOPE_WORKGROUP); } }
.LBB0_763:
	v_cndmask_b32_e64 v19, 0, 1, s[90:91]
	v_cmp_ne_u32_e64 s[0:1], 1, v19
	s_andn2_b64 vcc, exec, s[90:91]
	s_nop 0
	v_writelane_b32 v253, s0, 7
	s_nop 1
	v_writelane_b32 v253, s1, 8
	s_cbranch_vccnz .LBB0_773
	v_and_b32_e32 v19, s55, v87
	v_cmp_eq_u32_e32 vcc, v19, v1
	v_bfe_u32 v19, v87, s54, 8
	v_lshl_add_u32 v19, v19, 2, v21
	v_cndmask_b32_e32 v19, v248, v19, vcc
	ds_add_u32 v19, v172 offset:34816
	v_and_b32_e32 v19, s55, v89
	v_cmp_eq_u32_e32 vcc, v19, v1
	v_bfe_u32 v19, v89, s54, 8
	v_lshl_add_u32 v19, v19, 2, v21
	v_cndmask_b32_e32 v19, v248, v19, vcc
	ds_add_u32 v19, v172 offset:34816
	v_and_b32_e32 v19, s55, v88
	v_cmp_eq_u32_e32 vcc, v19, v1
	v_bfe_u32 v19, v88, s54, 8
	v_lshl_add_u32 v19, v19, 2, v21
	v_cndmask_b32_e32 v19, v248, v19, vcc
	ds_add_u32 v19, v172 offset:34816
	v_and_b32_e32 v19, s55, v90
	v_cmp_eq_u32_e32 vcc, v19, v1
	v_bfe_u32 v19, v90, s54, 8
	v_lshl_add_u32 v19, v19, 2, v21
	v_cndmask_b32_e32 v19, v248, v19, vcc
	ds_add_u32 v19, v172 offset:34816
.LBB0_773:
	v_cndmask_b32_e64 v19, 0, 1, s[4:5]
	v_cmp_ne_u32_e64 s[0:1], 1, v19
	s_andn2_b64 vcc, exec, s[4:5]
	s_nop 0
	v_writelane_b32 v253, s0, 9
	s_nop 1
	v_writelane_b32 v253, s1, 10
	s_cbranch_vccnz .LBB0_783
	v_and_b32_e32 v19, s55, v85
	v_cmp_eq_u32_e32 vcc, v19, v1
	v_bfe_u32 v19, v85, s54, 8
	v_lshl_add_u32 v19, v19, 2, v21
	v_cndmask_b32_e32 v19, v248, v19, vcc
	ds_add_u32 v19, v172 offset:34816
	v_and_b32_e32 v19, s55, v84
	v_cmp_eq_u32_e32 vcc, v19, v1
	v_bfe_u32 v19, v84, s54, 8
	v_lshl_add_u32 v19, v19, 2, v21
	v_cndmask_b32_e32 v19, v248, v19, vcc
	ds_add_u32 v19, v172 offset:34816
	v_and_b32_e32 v19, s55, v83
	v_cmp_eq_u32_e32 vcc, v19, v1
	v_bfe_u32 v19, v83, s54, 8
	v_lshl_add_u32 v19, v19, 2, v21
	v_cndmask_b32_e32 v19, v248, v19, vcc
	ds_add_u32 v19, v172 offset:34816
	v_and_b32_e32 v19, s55, v86
	v_cmp_eq_u32_e32 vcc, v19, v1
	v_bfe_u32 v19, v86, s54, 8
	v_lshl_add_u32 v19, v19, 2, v21
	v_cndmask_b32_e32 v19, v248, v19, vcc
	ds_add_u32 v19, v172 offset:34816
.LBB0_783:
	v_cndmask_b32_e64 v19, 0, 1, s[6:7]
	v_cmp_ne_u32_e64 s[0:1], 1, v19
	s_andn2_b64 vcc, exec, s[6:7]
	s_nop 0
	v_writelane_b32 v253, s0, 11
	s_nop 1
	v_writelane_b32 v253, s1, 12
	s_cbranch_vccnz .LBB0_793
	v_and_b32_e32 v19, s55, v79
	v_cmp_eq_u32_e32 vcc, v19, v1
	v_bfe_u32 v19, v79, s54, 8
	v_lshl_add_u32 v19, v19, 2, v21
	v_cndmask_b32_e32 v19, v248, v19, vcc
	ds_add_u32 v19, v172 offset:34816
	v_and_b32_e32 v19, s55, v81
	v_cmp_eq_u32_e32 vcc, v19, v1
	v_bfe_u32 v19, v81, s54, 8
	v_lshl_add_u32 v19, v19, 2, v21
	v_cndmask_b32_e32 v19, v248, v19, vcc
	ds_add_u32 v19, v172 offset:34816
	v_and_b32_e32 v19, s55, v80
	v_cmp_eq_u32_e32 vcc, v19, v1
	v_bfe_u32 v19, v80, s54, 8
	v_lshl_add_u32 v19, v19, 2, v21
	v_cndmask_b32_e32 v19, v248, v19, vcc
	ds_add_u32 v19, v172 offset:34816
	v_and_b32_e32 v19, s55, v82
	v_cmp_eq_u32_e32 vcc, v19, v1
	v_bfe_u32 v19, v82, s54, 8
	v_lshl_add_u32 v19, v19, 2, v21
	v_cndmask_b32_e32 v19, v248, v19, vcc
	ds_add_u32 v19, v172 offset:34816
.LBB0_793:
	v_cndmask_b32_e64 v19, 0, 1, s[8:9]
	v_cmp_ne_u32_e64 s[0:1], 1, v19
	s_andn2_b64 vcc, exec, s[8:9]
	s_nop 0
	v_writelane_b32 v253, s0, 13
	s_nop 1
	v_writelane_b32 v253, s1, 14
	s_cbranch_vccnz .LBB0_803
	v_and_b32_e32 v19, s55, v77
	v_cmp_eq_u32_e32 vcc, v19, v1
	v_bfe_u32 v19, v77, s54, 8
	v_lshl_add_u32 v19, v19, 2, v21
	v_cndmask_b32_e32 v19, v248, v19, vcc
	ds_add_u32 v19, v172 offset:34816
	v_and_b32_e32 v19, s55, v76
	v_cmp_eq_u32_e32 vcc, v19, v1
	v_bfe_u32 v19, v76, s54, 8
	v_lshl_add_u32 v19, v19, 2, v21
	v_cndmask_b32_e32 v19, v248, v19, vcc
	ds_add_u32 v19, v172 offset:34816
	v_and_b32_e32 v19, s55, v75
	v_cmp_eq_u32_e32 vcc, v19, v1
	v_bfe_u32 v19, v75, s54, 8
	v_lshl_add_u32 v19, v19, 2, v21
	v_cndmask_b32_e32 v19, v248, v19, vcc
	ds_add_u32 v19, v172 offset:34816
	v_and_b32_e32 v19, s55, v78
	v_cmp_eq_u32_e32 vcc, v19, v1
	v_bfe_u32 v19, v78, s54, 8
	v_lshl_add_u32 v19, v19, 2, v21
	v_cndmask_b32_e32 v19, v248, v19, vcc
	ds_add_u32 v19, v172 offset:34816
.LBB0_803:
	v_cndmask_b32_e64 v19, 0, 1, s[10:11]
	v_cmp_ne_u32_e64 s[0:1], 1, v19
	s_andn2_b64 vcc, exec, s[10:11]
	s_nop 0
	v_writelane_b32 v253, s0, 15
	s_nop 1
	v_writelane_b32 v253, s1, 16
	s_cbranch_vccnz .LBB0_813
	v_and_b32_e32 v19, s55, v71
	v_cmp_eq_u32_e32 vcc, v19, v1
	v_bfe_u32 v19, v71, s54, 8
	v_lshl_add_u32 v19, v19, 2, v21
	v_cndmask_b32_e32 v19, v248, v19, vcc
	ds_add_u32 v19, v172 offset:34816
	v_and_b32_e32 v19, s55, v73
	v_cmp_eq_u32_e32 vcc, v19, v1
	v_bfe_u32 v19, v73, s54, 8
	v_lshl_add_u32 v19, v19, 2, v21
	v_cndmask_b32_e32 v19, v248, v19, vcc
	ds_add_u32 v19, v172 offset:34816
	v_and_b32_e32 v19, s55, v72
	v_cmp_eq_u32_e32 vcc, v19, v1
	v_bfe_u32 v19, v72, s54, 8
	v_lshl_add_u32 v19, v19, 2, v21
	v_cndmask_b32_e32 v19, v248, v19, vcc
	ds_add_u32 v19, v172 offset:34816
	v_and_b32_e32 v19, s55, v74
	v_cmp_eq_u32_e32 vcc, v19, v1
	v_bfe_u32 v19, v74, s54, 8
	v_lshl_add_u32 v19, v19, 2, v21
	v_cndmask_b32_e32 v19, v248, v19, vcc
	ds_add_u32 v19, v172 offset:34816
.LBB0_813:
	v_cndmask_b32_e64 v19, 0, 1, s[12:13]
	v_cmp_ne_u32_e64 s[0:1], 1, v19
	s_andn2_b64 vcc, exec, s[12:13]
	s_nop 0
	v_writelane_b32 v253, s0, 17
	s_nop 1
	v_writelane_b32 v253, s1, 18
	s_cbranch_vccnz .LBB0_823
	v_and_b32_e32 v19, s55, v67
	v_cmp_eq_u32_e32 vcc, v19, v1
	v_bfe_u32 v19, v67, s54, 8
	v_lshl_add_u32 v19, v19, 2, v21
	v_cndmask_b32_e32 v19, v248, v19, vcc
	ds_add_u32 v19, v172 offset:34816
	v_and_b32_e32 v19, s55, v69
	v_cmp_eq_u32_e32 vcc, v19, v1
	v_bfe_u32 v19, v69, s54, 8
	v_lshl_add_u32 v19, v19, 2, v21
	v_cndmask_b32_e32 v19, v248, v19, vcc
	ds_add_u32 v19, v172 offset:34816
	v_and_b32_e32 v19, s55, v68
	v_cmp_eq_u32_e32 vcc, v19, v1
	v_bfe_u32 v19, v68, s54, 8
	v_lshl_add_u32 v19, v19, 2, v21
	v_cndmask_b32_e32 v19, v248, v19, vcc
	ds_add_u32 v19, v172 offset:34816
	v_and_b32_e32 v19, s55, v70
	v_cmp_eq_u32_e32 vcc, v19, v1
	v_bfe_u32 v19, v70, s54, 8
	v_lshl_add_u32 v19, v19, 2, v21
	v_cndmask_b32_e32 v19, v248, v19, vcc
	ds_add_u32 v19, v172 offset:34816
; DI void select_unit(unsigned char* ws, LAS unsigned char* lds, int b, int blk, const float* scratch, int wave) {
;     ...
;             for (int j = 0; j < 32; ++j) if (64 * j < n4) {
; #pragma unroll
;                 for (int c = 0; c < 4; ++c) { const unsigned u = key[j][c]; if ((u & pmask) == prefix) __hip_atomic_fetch_add(hc + ((u >> shift) & 255u), 1u, __ATOMIC_RELAXED, __HIP_MEMORY_SCOPE_WORKGROUP); } }
.LBB0_823:
	v_cndmask_b32_e64 v19, 0, 1, s[14:15]
	v_cmp_ne_u32_e64 s[0:1], 1, v19
	s_andn2_b64 vcc, exec, s[14:15]
	s_nop 0
	v_writelane_b32 v253, s0, 19
	s_nop 1
	v_writelane_b32 v253, s1, 20
	s_cbranch_vccnz .LBB0_833
	v_and_b32_e32 v19, s55, v63
	v_cmp_eq_u32_e32 vcc, v19, v1
	v_bfe_u32 v19, v63, s54, 8
	v_lshl_add_u32 v19, v19, 2, v21
	v_cndmask_b32_e32 v19, v248, v19, vcc
	ds_add_u32 v19, v172 offset:34816
	v_and_b32_e32 v19, s55, v65
	v_cmp_eq_u32_e32 vcc, v19, v1
	v_bfe_u32 v19, v65, s54, 8
	v_lshl_add_u32 v19, v19, 2, v21
	v_cndmask_b32_e32 v19, v248, v19, vcc
	ds_add_u32 v19, v172 offset:34816
	v_and_b32_e32 v19, s55, v64
	v_cmp_eq_u32_e32 vcc, v19, v1
	v_bfe_u32 v19, v64, s54, 8
	v_lshl_add_u32 v19, v19, 2, v21
	v_cndmask_b32_e32 v19, v248, v19, vcc
	ds_add_u32 v19, v172 offset:34816
	v_and_b32_e32 v19, s55, v66
	v_cmp_eq_u32_e32 vcc, v19, v1
	v_bfe_u32 v19, v66, s54, 8
	v_lshl_add_u32 v19, v19, 2, v21
	v_cndmask_b32_e32 v19, v248, v19, vcc
	ds_add_u32 v19, v172 offset:34816
.LBB0_833:
	v_cndmask_b32_e64 v19, 0, 1, s[16:17]
	v_cmp_ne_u32_e64 s[0:1], 1, v19
	s_andn2_b64 vcc, exec, s[16:17]
	s_nop 0
	v_writelane_b32 v253, s0, 21
	s_nop 1
	v_writelane_b32 v253, s1, 22
	s_cbranch_vccnz .LBB0_843
	v_and_b32_e32 v19, s55, v60
	v_cmp_eq_u32_e32 vcc, v19, v1
	v_bfe_u32 v19, v60, s54, 8
	v_lshl_add_u32 v19, v19, 2, v21
	v_cndmask_b32_e32 v19, v248, v19, vcc
	ds_add_u32 v19, v172 offset:34816
	v_and_b32_e32 v19, s55, v59
	v_cmp_eq_u32_e32 vcc, v19, v1
	v_bfe_u32 v19, v59, s54, 8
	v_lshl_add_u32 v19, v19, 2, v21
	v_cndmask_b32_e32 v19, v248, v19, vcc
	ds_add_u32 v19, v172 offset:34816
	v_and_b32_e32 v19, s55, v61
	v_cmp_eq_u32_e32 vcc, v19, v1
	v_bfe_u32 v19, v61, s54, 8
	v_lshl_add_u32 v19, v19, 2, v21
	v_cndmask_b32_e32 v19, v248, v19, vcc
	ds_add_u32 v19, v172 offset:34816
	v_and_b32_e32 v19, s55, v62
	v_cmp_eq_u32_e32 vcc, v19, v1
	v_bfe_u32 v19, v62, s54, 8
	v_lshl_add_u32 v19, v19, 2, v21
	v_cndmask_b32_e32 v19, v248, v19, vcc
	ds_add_u32 v19, v172 offset:34816
.LBB0_843:
	v_cndmask_b32_e64 v19, 0, 1, s[82:83]
	v_cmp_ne_u32_e64 s[0:1], 1, v19
	s_andn2_b64 vcc, exec, s[82:83]
	s_nop 0
	v_writelane_b32 v253, s0, 23
	s_nop 1
	v_writelane_b32 v253, s1, 24
	s_cbranch_vccnz .LBB0_853
	v_and_b32_e32 v19, s55, v55
	v_cmp_eq_u32_e32 vcc, v19, v1
	v_bfe_u32 v19, v55, s54, 8
	v_lshl_add_u32 v19, v19, 2, v21
	v_cndmask_b32_e32 v19, v248, v19, vcc
	ds_add_u32 v19, v172 offset:34816
	v_and_b32_e32 v19, s55, v57
	v_cmp_eq_u32_e32 vcc, v19, v1
	v_bfe_u32 v19, v57, s54, 8
	v_lshl_add_u32 v19, v19, 2, v21
	v_cndmask_b32_e32 v19, v248, v19, vcc
	ds_add_u32 v19, v172 offset:34816
	v_and_b32_e32 v19, s55, v56
	v_cmp_eq_u32_e32 vcc, v19, v1
	v_bfe_u32 v19, v56, s54, 8
	v_lshl_add_u32 v19, v19, 2, v21
	v_cndmask_b32_e32 v19, v248, v19, vcc
	ds_add_u32 v19, v172 offset:34816
	v_and_b32_e32 v19, s55, v58
	v_cmp_eq_u32_e32 vcc, v19, v1
	v_bfe_u32 v19, v58, s54, 8
	v_lshl_add_u32 v19, v19, 2, v21
	v_cndmask_b32_e32 v19, v248, v19, vcc
	ds_add_u32 v19, v172 offset:34816
.LBB0_853:
	v_cndmask_b32_e64 v19, 0, 1, s[20:21]
	v_cmp_ne_u32_e64 s[0:1], 1, v19
	s_andn2_b64 vcc, exec, s[20:21]
	s_nop 0
	v_writelane_b32 v253, s0, 25
	s_nop 1
	v_writelane_b32 v253, s1, 26
	s_cbranch_vccnz .LBB0_863
	v_and_b32_e32 v19, s55, v51
	v_cmp_eq_u32_e32 vcc, v19, v1
	v_bfe_u32 v19, v51, s54, 8
	v_lshl_add_u32 v19, v19, 2, v21
	v_cndmask_b32_e32 v19, v248, v19, vcc
	ds_add_u32 v19, v172 offset:34816
	v_and_b32_e32 v19, s55, v53
	v_cmp_eq_u32_e32 vcc, v19, v1
	v_bfe_u32 v19, v53, s54, 8
	v_lshl_add_u32 v19, v19, 2, v21
	v_cndmask_b32_e32 v19, v248, v19, vcc
	ds_add_u32 v19, v172 offset:34816
	v_and_b32_e32 v19, s55, v52
	v_cmp_eq_u32_e32 vcc, v19, v1
	v_bfe_u32 v19, v52, s54, 8
	v_lshl_add_u32 v19, v19, 2, v21
	v_cndmask_b32_e32 v19, v248, v19, vcc
	ds_add_u32 v19, v172 offset:34816
	v_and_b32_e32 v19, s55, v54
	v_cmp_eq_u32_e32 vcc, v19, v1
	v_bfe_u32 v19, v54, s54, 8
	v_lshl_add_u32 v19, v19, 2, v21
	v_cndmask_b32_e32 v19, v248, v19, vcc
	ds_add_u32 v19, v172 offset:34816
.LBB0_863:
	v_cndmask_b32_e64 v19, 0, 1, s[22:23]
	v_cmp_ne_u32_e64 s[0:1], 1, v19
	s_andn2_b64 vcc, exec, s[22:23]
	s_nop 0
	v_writelane_b32 v253, s0, 27
	s_nop 1
	v_writelane_b32 v253, s1, 28
	s_cbranch_vccnz .LBB0_873
	v_and_b32_e32 v19, s55, v47
	v_cmp_eq_u32_e32 vcc, v19, v1
	v_bfe_u32 v19, v47, s54, 8
	v_lshl_add_u32 v19, v19, 2, v21
	v_cndmask_b32_e32 v19, v248, v19, vcc
	ds_add_u32 v19, v172 offset:34816
	v_and_b32_e32 v19, s55, v49
	v_cmp_eq_u32_e32 vcc, v19, v1
	v_bfe_u32 v19, v49, s54, 8
	v_lshl_add_u32 v19, v19, 2, v21
	v_cndmask_b32_e32 v19, v248, v19, vcc
	ds_add_u32 v19, v172 offset:34816
	v_and_b32_e32 v19, s55, v48
	v_cmp_eq_u32_e32 vcc, v19, v1
	v_bfe_u32 v19, v48, s54, 8
	v_lshl_add_u32 v19, v19, 2, v21
	v_cndmask_b32_e32 v19, v248, v19, vcc
	ds_add_u32 v19, v172 offset:34816
	v_and_b32_e32 v19, s55, v50
	v_cmp_eq_u32_e32 vcc, v19, v1
	v_bfe_u32 v19, v50, s54, 8
	v_lshl_add_u32 v19, v19, 2, v21
	v_cndmask_b32_e32 v19, v248, v19, vcc
	ds_add_u32 v19, v172 offset:34816
.LBB0_873:
	v_cndmask_b32_e64 v19, 0, 1, s[24:25]
	v_cmp_ne_u32_e64 s[0:1], 1, v19
	s_andn2_b64 vcc, exec, s[24:25]
	s_nop 0
	v_writelane_b32 v253, s0, 29
	s_nop 1
	v_writelane_b32 v253, s1, 30
	s_cbranch_vccnz .LBB0_883
	v_and_b32_e32 v19, s55, v42
	v_cmp_eq_u32_e32 vcc, v19, v1
	v_bfe_u32 v19, v42, s54, 8
	v_lshl_add_u32 v19, v19, 2, v21
	v_cndmask_b32_e32 v19, v248, v19, vcc
	ds_add_u32 v19, v172 offset:34816
	v_and_b32_e32 v19, s55, v44
	v_cmp_eq_u32_e32 vcc, v19, v1
	v_bfe_u32 v19, v44, s54, 8
	v_lshl_add_u32 v19, v19, 2, v21
	v_cndmask_b32_e32 v19, v248, v19, vcc
	ds_add_u32 v19, v172 offset:34816
	v_and_b32_e32 v19, s55, v43
	v_cmp_eq_u32_e32 vcc, v19, v1
	v_bfe_u32 v19, v43, s54, 8
	v_lshl_add_u32 v19, v19, 2, v21
	v_cndmask_b32_e32 v19, v248, v19, vcc
	ds_add_u32 v19, v172 offset:34816
	v_and_b32_e32 v19, s55, v45
	v_cmp_eq_u32_e32 vcc, v19, v1
	v_bfe_u32 v19, v45, s54, 8
	v_lshl_add_u32 v19, v19, 2, v21
	v_cndmask_b32_e32 v19, v248, v19, vcc
	ds_add_u32 v19, v172 offset:34816
; DI void select_unit(unsigned char* ws, LAS unsigned char* lds, int b, int blk, const float* scratch, int wave) {
;     ...
;             for (int j = 0; j < 32; ++j) if (64 * j < n4) {
; #pragma unroll
;                 for (int c = 0; c < 4; ++c) { const unsigned u = key[j][c]; if ((u & pmask) == prefix) __hip_atomic_fetch_add(hc + ((u >> shift) & 255u), 1u, __ATOMIC_RELAXED, __HIP_MEMORY_SCOPE_WORKGROUP); } }
.LBB0_883:
	v_cndmask_b32_e64 v19, 0, 1, s[26:27]
	v_cmp_ne_u32_e64 s[0:1], 1, v19
	s_andn2_b64 vcc, exec, s[26:27]
	s_nop 0
	v_writelane_b32 v253, s0, 31
	s_nop 1
	v_writelane_b32 v253, s1, 32
	s_cbranch_vccnz .LBB0_893
	v_and_b32_e32 v19, s55, v38
	v_cmp_eq_u32_e32 vcc, v19, v1
	v_bfe_u32 v19, v38, s54, 8
	v_lshl_add_u32 v19, v19, 2, v21
	v_cndmask_b32_e32 v19, v248, v19, vcc
	ds_add_u32 v19, v172 offset:34816
	v_and_b32_e32 v19, s55, v40
	v_cmp_eq_u32_e32 vcc, v19, v1
	v_bfe_u32 v19, v40, s54, 8
	v_lshl_add_u32 v19, v19, 2, v21
	v_cndmask_b32_e32 v19, v248, v19, vcc
	ds_add_u32 v19, v172 offset:34816
	v_and_b32_e32 v19, s55, v39
	v_cmp_eq_u32_e32 vcc, v19, v1
	v_bfe_u32 v19, v39, s54, 8
	v_lshl_add_u32 v19, v19, 2, v21
	v_cndmask_b32_e32 v19, v248, v19, vcc
	ds_add_u32 v19, v172 offset:34816
	v_and_b32_e32 v19, s55, v41
	v_cmp_eq_u32_e32 vcc, v19, v1
	v_bfe_u32 v19, v41, s54, 8
	v_lshl_add_u32 v19, v19, 2, v21
	v_cndmask_b32_e32 v19, v248, v19, vcc
	ds_add_u32 v19, v172 offset:34816
.LBB0_893:
	v_cndmask_b32_e64 v19, 0, 1, s[28:29]
	v_cmp_ne_u32_e64 s[0:1], 1, v19
	s_andn2_b64 vcc, exec, s[28:29]
	s_nop 0
	v_writelane_b32 v253, s0, 33
	s_nop 1
	v_writelane_b32 v253, s1, 34
	s_cbranch_vccnz .LBB0_903
	v_and_b32_e32 v19, s55, v34
	v_cmp_eq_u32_e32 vcc, v19, v1
	v_bfe_u32 v19, v34, s54, 8
	v_lshl_add_u32 v19, v19, 2, v21
	v_cndmask_b32_e32 v19, v248, v19, vcc
	ds_add_u32 v19, v172 offset:34816
	v_and_b32_e32 v19, s55, v36
	v_cmp_eq_u32_e32 vcc, v19, v1
	v_bfe_u32 v19, v36, s54, 8
	v_lshl_add_u32 v19, v19, 2, v21
	v_cndmask_b32_e32 v19, v248, v19, vcc
	ds_add_u32 v19, v172 offset:34816
	v_and_b32_e32 v19, s55, v35
	v_cmp_eq_u32_e32 vcc, v19, v1
	v_bfe_u32 v19, v35, s54, 8
	v_lshl_add_u32 v19, v19, 2, v21
	v_cndmask_b32_e32 v19, v248, v19, vcc
	ds_add_u32 v19, v172 offset:34816
	v_and_b32_e32 v19, s55, v37
	v_cmp_eq_u32_e32 vcc, v19, v1
	v_bfe_u32 v19, v37, s54, 8
	v_lshl_add_u32 v19, v19, 2, v21
	v_cndmask_b32_e32 v19, v248, v19, vcc
	ds_add_u32 v19, v172 offset:34816
.LBB0_903:
	v_cndmask_b32_e64 v19, 0, 1, s[30:31]
	v_cmp_ne_u32_e64 s[0:1], 1, v19
	s_andn2_b64 vcc, exec, s[30:31]
	s_nop 0
	v_writelane_b32 v253, s0, 35
	s_nop 1
	v_writelane_b32 v253, s1, 36
	s_cbranch_vccnz .LBB0_913
	v_and_b32_e32 v19, s55, v30
	v_cmp_eq_u32_e32 vcc, v19, v1
	v_bfe_u32 v19, v30, s54, 8
	v_lshl_add_u32 v19, v19, 2, v21
	v_cndmask_b32_e32 v19, v248, v19, vcc
	ds_add_u32 v19, v172 offset:34816
	v_and_b32_e32 v19, s55, v32
	v_cmp_eq_u32_e32 vcc, v19, v1
	v_bfe_u32 v19, v32, s54, 8
	v_lshl_add_u32 v19, v19, 2, v21
	v_cndmask_b32_e32 v19, v248, v19, vcc
	ds_add_u32 v19, v172 offset:34816
	v_and_b32_e32 v19, s55, v31
	v_cmp_eq_u32_e32 vcc, v19, v1
	v_bfe_u32 v19, v31, s54, 8
	v_lshl_add_u32 v19, v19, 2, v21
	v_cndmask_b32_e32 v19, v248, v19, vcc
	ds_add_u32 v19, v172 offset:34816
	v_and_b32_e32 v19, s55, v33
	v_cmp_eq_u32_e32 vcc, v19, v1
	v_bfe_u32 v19, v33, s54, 8
	v_lshl_add_u32 v19, v19, 2, v21
	v_cndmask_b32_e32 v19, v248, v19, vcc
	ds_add_u32 v19, v172 offset:34816
.LBB0_913:
	v_cndmask_b32_e64 v19, 0, 1, s[34:35]
	v_cmp_ne_u32_e64 s[0:1], 1, v19
	s_andn2_b64 vcc, exec, s[34:35]
	s_nop 0
	v_writelane_b32 v253, s0, 37
	s_nop 1
	v_writelane_b32 v253, s1, 38
	s_cbranch_vccnz .LBB0_923
	v_and_b32_e32 v19, s55, v27
	v_cmp_eq_u32_e32 vcc, v19, v1
	v_bfe_u32 v19, v27, s54, 8
	v_lshl_add_u32 v19, v19, 2, v21
	v_cndmask_b32_e32 v19, v248, v19, vcc
	ds_add_u32 v19, v172 offset:34816
	v_and_b32_e32 v19, s55, v26
	v_cmp_eq_u32_e32 vcc, v19, v1
	v_bfe_u32 v19, v26, s54, 8
	v_lshl_add_u32 v19, v19, 2, v21
	v_cndmask_b32_e32 v19, v248, v19, vcc
	ds_add_u32 v19, v172 offset:34816
	v_and_b32_e32 v19, s55, v28
	v_cmp_eq_u32_e32 vcc, v19, v1
	v_bfe_u32 v19, v28, s54, 8
	v_lshl_add_u32 v19, v19, 2, v21
	v_cndmask_b32_e32 v19, v248, v19, vcc
	ds_add_u32 v19, v172 offset:34816
	v_and_b32_e32 v19, s55, v29
	v_cmp_eq_u32_e32 vcc, v19, v1
	v_bfe_u32 v19, v29, s54, 8
	v_lshl_add_u32 v19, v19, 2, v21
	v_cndmask_b32_e32 v19, v248, v19, vcc
	ds_add_u32 v19, v172 offset:34816
; DI void select_unit(unsigned char* ws, LAS unsigned char* lds, int b, int blk, const float* scratch, int wave) {
;     ...
;             for (int j = 0; j < 32; ++j) if (64 * j < n4) {
; #pragma unroll
;                 for (int c = 0; c < 4; ++c) { const unsigned u = key[j][c]; if ((u & pmask) == prefix) __hip_atomic_fetch_add(hc + ((u >> shift) & 255u), 1u, __ATOMIC_RELAXED, __HIP_MEMORY_SCOPE_WORKGROUP); } }
.LBB0_923:
	v_cndmask_b32_e64 v19, 0, 1, s[36:37]
	v_cmp_ne_u32_e64 s[0:1], 1, v19
	s_andn2_b64 vcc, exec, s[36:37]
	s_nop 0
	v_writelane_b32 v253, s0, 39
	s_nop 1
	v_writelane_b32 v253, s1, 40
	s_cbranch_vccnz .LBB0_933
	v_and_b32_e32 v19, s55, v20
	v_cmp_eq_u32_e32 vcc, v19, v1
	v_bfe_u32 v19, v20, s54, 8
	v_lshl_add_u32 v19, v19, 2, v21
	v_cndmask_b32_e32 v19, v248, v19, vcc
	ds_add_u32 v19, v172 offset:34816
	v_and_b32_e32 v19, s55, v24
	v_cmp_eq_u32_e32 vcc, v19, v1
	v_bfe_u32 v19, v24, s54, 8
	v_lshl_add_u32 v19, v19, 2, v21
	v_cndmask_b32_e32 v19, v248, v19, vcc
	ds_add_u32 v19, v172 offset:34816
	v_and_b32_e32 v19, s55, v23
	v_cmp_eq_u32_e32 vcc, v19, v1
	v_bfe_u32 v19, v23, s54, 8
	v_lshl_add_u32 v19, v19, 2, v21
	v_cndmask_b32_e32 v19, v248, v19, vcc
	ds_add_u32 v19, v172 offset:34816
	v_and_b32_e32 v19, s55, v25
	v_cmp_eq_u32_e32 vcc, v19, v1
	v_bfe_u32 v19, v25, s54, 8
	v_lshl_add_u32 v19, v19, 2, v21
	v_cndmask_b32_e32 v19, v248, v19, vcc
	ds_add_u32 v19, v172 offset:34816
.LBB0_933:
	v_cndmask_b32_e64 v19, 0, 1, s[38:39]
	v_cmp_ne_u32_e64 s[0:1], 1, v19
	s_andn2_b64 vcc, exec, s[38:39]
	s_nop 0
	v_writelane_b32 v253, s0, 41
	s_nop 1
	v_writelane_b32 v253, s1, 42
	s_cbranch_vccnz .LBB0_943
	v_and_b32_e32 v19, s55, v15
	v_cmp_eq_u32_e32 vcc, v19, v1
	v_bfe_u32 v19, v15, s54, 8
	v_lshl_add_u32 v19, v19, 2, v21
	v_cndmask_b32_e32 v19, v248, v19, vcc
	ds_add_u32 v19, v172 offset:34816
	v_and_b32_e32 v19, s55, v17
	v_cmp_eq_u32_e32 vcc, v19, v1
	v_bfe_u32 v19, v17, s54, 8
	v_lshl_add_u32 v19, v19, 2, v21
	v_cndmask_b32_e32 v19, v248, v19, vcc
	ds_add_u32 v19, v172 offset:34816
	v_and_b32_e32 v19, s55, v16
	v_cmp_eq_u32_e32 vcc, v19, v1
	v_bfe_u32 v19, v16, s54, 8
	v_lshl_add_u32 v19, v19, 2, v21
	v_cndmask_b32_e32 v19, v248, v19, vcc
	ds_add_u32 v19, v172 offset:34816
	v_and_b32_e32 v19, s55, v18
	v_cmp_eq_u32_e32 vcc, v19, v1
	v_bfe_u32 v19, v18, s54, 8
	v_lshl_add_u32 v19, v19, 2, v21
	v_cndmask_b32_e32 v19, v248, v19, vcc
	ds_add_u32 v19, v172 offset:34816
.LBB0_943:
	v_cndmask_b32_e64 v19, 0, 1, s[40:41]
	v_cmp_ne_u32_e64 s[0:1], 1, v19
	s_andn2_b64 vcc, exec, s[40:41]
	s_nop 0
	v_writelane_b32 v253, s0, 43
	s_nop 1
	v_writelane_b32 v253, s1, 44
	s_cbranch_vccnz .LBB0_953
	v_and_b32_e32 v19, s55, v11
	v_cmp_eq_u32_e32 vcc, v19, v1
	v_bfe_u32 v19, v11, s54, 8
	v_lshl_add_u32 v19, v19, 2, v21
	v_cndmask_b32_e32 v19, v248, v19, vcc
	ds_add_u32 v19, v172 offset:34816
	v_and_b32_e32 v19, s55, v13
	v_cmp_eq_u32_e32 vcc, v19, v1
	v_bfe_u32 v19, v13, s54, 8
	v_lshl_add_u32 v19, v19, 2, v21
	v_cndmask_b32_e32 v19, v248, v19, vcc
	ds_add_u32 v19, v172 offset:34816
	v_and_b32_e32 v19, s55, v12
	v_cmp_eq_u32_e32 vcc, v19, v1
	v_bfe_u32 v19, v12, s54, 8
	v_lshl_add_u32 v19, v19, 2, v21
	v_cndmask_b32_e32 v19, v248, v19, vcc
	ds_add_u32 v19, v172 offset:34816
	v_and_b32_e32 v19, s55, v14
	v_cmp_eq_u32_e32 vcc, v19, v1
	v_bfe_u32 v19, v14, s54, 8
	v_lshl_add_u32 v19, v19, 2, v21
	v_cndmask_b32_e32 v19, v248, v19, vcc
	ds_add_u32 v19, v172 offset:34816
.LBB0_953:
	v_cndmask_b32_e64 v19, 0, 1, s[42:43]
	v_cmp_ne_u32_e64 s[0:1], 1, v19
	s_andn2_b64 vcc, exec, s[42:43]
	s_nop 0
	v_writelane_b32 v253, s0, 45
	s_nop 1
	v_writelane_b32 v253, s1, 46
	s_cbranch_vccnz .LBB0_963
	v_and_b32_e32 v19, s55, v7
	v_cmp_eq_u32_e32 vcc, v19, v1
	v_bfe_u32 v19, v7, s54, 8
	v_lshl_add_u32 v19, v19, 2, v21
	v_cndmask_b32_e32 v19, v248, v19, vcc
	ds_add_u32 v19, v172 offset:34816
	v_and_b32_e32 v19, s55, v9
	v_cmp_eq_u32_e32 vcc, v19, v1
	v_bfe_u32 v19, v9, s54, 8
	v_lshl_add_u32 v19, v19, 2, v21
	v_cndmask_b32_e32 v19, v248, v19, vcc
	ds_add_u32 v19, v172 offset:34816
	v_and_b32_e32 v19, s55, v8
	v_cmp_eq_u32_e32 vcc, v19, v1
	v_bfe_u32 v19, v8, s54, 8
	v_lshl_add_u32 v19, v19, 2, v21
	v_cndmask_b32_e32 v19, v248, v19, vcc
	ds_add_u32 v19, v172 offset:34816
	v_and_b32_e32 v19, s55, v10
	v_cmp_eq_u32_e32 vcc, v19, v1
	v_bfe_u32 v19, v10, s54, 8
	v_lshl_add_u32 v19, v19, 2, v21
	v_cndmask_b32_e32 v19, v248, v19, vcc
	ds_add_u32 v19, v172 offset:34816
.LBB0_963:
	v_cndmask_b32_e64 v19, 0, 1, s[44:45]
	v_cmp_ne_u32_e64 s[0:1], 1, v19
	s_andn2_b64 vcc, exec, s[44:45]
	s_nop 0
	v_writelane_b32 v253, s0, 47
	s_nop 1
	v_writelane_b32 v253, s1, 48
	s_cbranch_vccnz .LBB0_973
	v_and_b32_e32 v19, s55, v3
	v_cmp_eq_u32_e32 vcc, v19, v1
	v_bfe_u32 v19, v3, s54, 8
	v_lshl_add_u32 v19, v19, 2, v21
	v_cndmask_b32_e32 v19, v248, v19, vcc
	ds_add_u32 v19, v172 offset:34816
	v_and_b32_e32 v19, s55, v5
	v_cmp_eq_u32_e32 vcc, v19, v1
	v_bfe_u32 v19, v5, s54, 8
	v_lshl_add_u32 v19, v19, 2, v21
	v_cndmask_b32_e32 v19, v248, v19, vcc
	ds_add_u32 v19, v172 offset:34816
	v_and_b32_e32 v19, s55, v4
	v_cmp_eq_u32_e32 vcc, v19, v1
	v_bfe_u32 v19, v4, s54, 8
	v_lshl_add_u32 v19, v19, 2, v21
	v_cndmask_b32_e32 v19, v248, v19, vcc
	ds_add_u32 v19, v172 offset:34816
	v_and_b32_e32 v19, s55, v6
	v_cmp_eq_u32_e32 vcc, v19, v1
	v_bfe_u32 v19, v6, s54, 8
	v_lshl_add_u32 v19, v19, 2, v21
	v_cndmask_b32_e32 v19, v248, v19, vcc
	ds_add_u32 v19, v172 offset:34816
